# combo15 + light seams: the acquire-side L1 invalidate is issued with the panel barrier's arrival atomic instead of after the poll (its completion overlaps the wait for the other workgroups)
# baseline (speedup 1.0000x reference)
; __device__ __forceinline__ unsigned xb_ld(unsigned* p)              { return __hip_atomic_load(p, __ATOMIC_RELAXED, __HIP_MEMORY_SCOPE_AGENT); }
; __device__ __forceinline__ unsigned xb_add(unsigned* p, unsigned v) { return __hip_atomic_fetch_add(p, v, __ATOMIC_RELAXED, __HIP_MEMORY_SCOPE_AGENT); }
; __device__ __forceinline__ void panel_barrier(unsigned* cnt, int tid) {
;     asm volatile("s_waitcnt vmcnt(0)" ::: "memory");
;     __syncthreads();
;     if (tid == 0) {
;         __builtin_amdgcn_s_waitcnt(0);
;         const unsigned old = xb_add(cnt, 1u), target = (old & ~3u) + 4u;
;         unsigned sp = 0u;
;         while (xb_ld(cnt) < target) { __builtin_amdgcn_s_sleep(1); if (++sp > (1u << 26)) break; }
;         __builtin_amdgcn_fence(__ATOMIC_ACQUIRE, "agent");
;         asm volatile("s_waitcnt vmcnt(0)" ::: "memory");
;     }
.LBB0_427:
	s_and_b64 vcc, exec, s[4:5]
	s_cbranch_vccz .LBB0_443
	v_readlane_b32 s0, v254, 1
	v_mbcnt_lo_u32_b32 v0, -1, 0
	v_mbcnt_hi_u32_b32 v0, -1, v0
	s_nop 1
	v_lshl_add_u32 v0, s0, 6, v0
	s_waitcnt vmcnt(0)
	s_waitcnt vmcnt(0) lgkmcnt(0)
	v_cmp_eq_u32_e32 vcc, 0, v0
	s_barrier
	s_and_saveexec_b64 s[4:5], vcc
	s_cbranch_execz .LBB0_442
	v_readlane_b32 s0, v254, 19
	s_lshl_b32 s0, s0, 2
	s_add_u32 s1, s92, s0
	s_addc_u32 s2, s93, 0
	v_mov_b32_e32 v0, s1
	v_add_co_u32_e32 v2, vcc, 0x12000, v0
	v_mov_b32_e32 v0, s2
	s_nop 0
	v_addc_co_u32_e32 v3, vcc, 0, v0, vcc
	s_waitcnt vmcnt(0) expcnt(0) lgkmcnt(0)
	flat_atomic_add v0, v[2:3], v210 offset:2048 sc0
	buffer_inv sc1
	s_add_u32 s6, s1, 0x12800
	s_mov_b32 s0, 0x4000001
	s_addc_u32 s7, s2, 0
	s_mov_b64 s[8:9], 0
	s_waitcnt vmcnt(0) lgkmcnt(0)
	v_and_b32_e32 v0, -4, v0
	v_add_u32_e32 v0, 4, v0
	s_branch .LBB0_435

; __device__ __forceinline__ unsigned xb_ld(unsigned* p)              { return __hip_atomic_load(p, __ATOMIC_RELAXED, __HIP_MEMORY_SCOPE_AGENT); }
; __device__ __forceinline__ unsigned xb_add(unsigned* p, unsigned v) { return __hip_atomic_fetch_add(p, v, __ATOMIC_RELAXED, __HIP_MEMORY_SCOPE_AGENT); }
; __device__ __forceinline__ void panel_barrier(unsigned* cnt, int tid) {
;     asm volatile("s_waitcnt vmcnt(0)" ::: "memory");
;     __syncthreads();
;     if (tid == 0) {
;         __builtin_amdgcn_s_waitcnt(0);
;         const unsigned old = xb_add(cnt, 1u), target = (old & ~3u) + 4u;
;         unsigned sp = 0u;
;         while (xb_ld(cnt) < target) { __builtin_amdgcn_s_sleep(1); if (++sp > (1u << 26)) break; }
;         __builtin_amdgcn_fence(__ATOMIC_ACQUIRE, "agent");
;         asm volatile("s_waitcnt vmcnt(0)" ::: "memory");
;     }
.LBB0_620:
	s_and_b64 vcc, exec, s[4:5]
	s_cbranch_vccz .LBB0_636
	v_readlane_b32 s0, v254, 1
	v_mbcnt_lo_u32_b32 v0, -1, 0
	v_mbcnt_hi_u32_b32 v0, -1, v0
	s_nop 1
	v_lshl_add_u32 v0, s0, 6, v0
	s_waitcnt vmcnt(0)
	s_nop 0
	v_cmp_eq_u32_e32 vcc, 0, v0
	s_barrier
	s_and_saveexec_b64 s[4:5], vcc
	s_cbranch_execz .LBB0_635
	v_readlane_b32 s0, v254, 54
	s_add_u32 s1, s92, s0
	s_addc_u32 s2, s93, 0
	v_mov_b32_e32 v0, s1
	v_add_co_u32_e32 v2, vcc, 0x12000, v0
	v_mov_b32_e32 v0, s2
	s_nop 0
	v_addc_co_u32_e32 v3, vcc, 0, v0, vcc
	s_waitcnt vmcnt(0) expcnt(0) lgkmcnt(0)
	flat_atomic_add v0, v[2:3], v210 offset:2048 sc0
	buffer_inv sc1
	s_add_u32 s6, s1, 0x12800
	s_mov_b32 s0, 0x4000001
	s_addc_u32 s7, s2, 0
	s_mov_b64 s[8:9], 0
	s_waitcnt vmcnt(0) lgkmcnt(0)
	v_and_b32_e32 v0, -4, v0
	v_add_u32_e32 v0, 4, v0
	s_branch .LBB0_628

; __device__ __forceinline__ unsigned xb_ld(unsigned* p)              { return __hip_atomic_load(p, __ATOMIC_RELAXED, __HIP_MEMORY_SCOPE_AGENT); }
; __device__ __forceinline__ unsigned xb_add(unsigned* p, unsigned v) { return __hip_atomic_fetch_add(p, v, __ATOMIC_RELAXED, __HIP_MEMORY_SCOPE_AGENT); }
; __device__ __forceinline__ void panel_barrier(unsigned* cnt, int tid) {
;     asm volatile("s_waitcnt vmcnt(0)" ::: "memory");
;     __syncthreads();
;     if (tid == 0) {
;         __builtin_amdgcn_s_waitcnt(0);
;         const unsigned old = xb_add(cnt, 1u), target = (old & ~3u) + 4u;
;         unsigned sp = 0u;
;         while (xb_ld(cnt) < target) { __builtin_amdgcn_s_sleep(1); if (++sp > (1u << 26)) break; }
;         __builtin_amdgcn_fence(__ATOMIC_ACQUIRE, "agent");
;         asm volatile("s_waitcnt vmcnt(0)" ::: "memory");
;     }
.LBB0_1430:
	s_and_b64 vcc, exec, s[0:1]
	s_cbranch_vccz .LBB0_306
	v_readlane_b32 s0, v254, 1
	v_mbcnt_lo_u32_b32 v0, -1, 0
	v_mbcnt_hi_u32_b32 v0, -1, v0
	s_nop 1
	v_lshl_add_u32 v0, s0, 6, v0
	s_waitcnt vmcnt(0)
	s_waitcnt vmcnt(0) lgkmcnt(0)
	v_cmp_eq_u32_e32 vcc, 0, v0
	s_barrier
	s_and_saveexec_b64 s[0:1], vcc
	s_cbranch_execz .LBB0_305
	v_readlane_b32 s2, v254, 19
	s_lshl_b32 s2, s2, 2
	s_add_u32 s2, s92, s2
	s_addc_u32 s3, s93, 0
	v_mov_b32_e32 v0, s2
	v_add_co_u32_e32 v2, vcc, 0x12000, v0
	v_mov_b32_e32 v0, s3
	s_nop 0
	v_addc_co_u32_e32 v3, vcc, 0, v0, vcc
	s_waitcnt vmcnt(0) expcnt(0) lgkmcnt(0)
	flat_atomic_add v0, v[2:3], v210 offset:2048 sc0
	buffer_inv sc1
	s_add_u32 s2, s2, 0x12800
	s_mov_b32 s20, 0x4000001
	s_addc_u32 s3, s3, 0
	s_mov_b64 s[4:5], 0
	s_waitcnt vmcnt(0) lgkmcnt(0)
	v_and_b32_e32 v0, -4, v0
	v_add_u32_e32 v0, 4, v0
	s_branch .LBB0_1438
